# dilated-merge rows rebalanced: only the 128 CUs whose NSA unit is light (q_blk<16) merge, 8 rows per wave; NSA-heavy CUs skip it
# speedup vs baseline: 1.0060x; 1.0022x over previous
.LBB0_1049:
	v_readlane_b32 s4, v254, 5
	v_readlane_b32 s5, v254, 6
	s_mov_b32 s1, s79
	v_mov_b32_e32 v0, v210
	s_mov_b32 s1, s79
	s_nop 0
	v_ashrrev_i32_e32 v2, 6, v0
	s_lshr_b32 s1, s79, 5
	s_lshl_b32 s1, s1, 4
	s_and_b32 s12, s79, 15
	s_or_b32 s1, s1, s12
	s_bitcmp1_b32 s79, 4
	s_cselect_b32 s1, 0x1000, s1
	v_lshl_add_u32 v6, s1, 3, v2
	s_movk_i32 s1, 0x2000
	v_cmp_gt_i32_e32 vcc, s1, v6
	s_and_saveexec_b64 s[2:3], vcc
	v_readlane_b32 s14, v255, 6
	v_readlane_b32 s20, v255, 13
	v_readlane_b32 s22, v255, 17
	v_readlane_b32 s12, v255, 15
	v_readlane_b32 s15, v255, 7
	v_readlane_b32 s21, v255, 14
	v_readlane_b32 s23, v255, 18
	v_readlane_b32 s13, v255, 16
	s_nop 3
	s_lshr_b32 s12, s12, 1
	s_lshr_b64 s[14:15], s[14:15], 1
	s_lshr_b64 s[20:21], s[20:21], 1
	s_lshr_b64 s[22:23], s[22:23], 1
	s_cbranch_execz .LBB0_1052
	s_load_dwordx2 s[18:19], s[4:5], 0x90
	v_bfe_u32 v4, v0, 4, 2
	s_movk_i32 s1, 0x1400
	v_lshlrev_b32_e32 v0, 4, v0
	v_ashrrev_i32_e32 v7, 31, v6
	v_mad_i64_i32 v[2:3], s[4:5], v6, s1, 0
	v_lshlrev_b32_e32 v5, 8, v4
	v_and_b32_e32 v0, 0xf0, v0
	v_or3_b32 v2, v2, v5, v0
	s_mov_b64 s[4:5], 0x2aa00800
	v_lshlrev_b64 v[10:11], 10, v[6:7]
	v_lshlrev_b64 v[12:13], 4, v[6:7]
	v_lshl_add_u64 v[8:9], v[2:3], 0, s[4:5]
	v_or3_b32 v10, v10, v5, v0
	v_lshl_or_b32 v12, v4, 2, v12
	s_mov_b64 s[30:31], 0
